# v100 plus only the next-unit Q touch (no gate / parked-O touches)
# speedup vs baseline: 1.0039x; 1.0039x over previous
.LBB0_688:
	v_mbcnt_lo_u32_b32 v212, -1, 0
	v_mbcnt_hi_u32_b32 v212, -1, v212
	v_lshrrev_b32_e32 v213, 5, v212
	v_and_b32_e32 v212, 31, v212
	s_lshr_b32 s52, s75, 1
	s_mov_b32 s54, s66
	s_cmp_eq_u32 s52, 1
	s_cselect_b32 s54, s61, s54
	s_cmp_eq_u32 s52, 2
	s_cselect_b32 s54, s63, s54
	s_cmp_eq_u32 s52, 3
	s_cselect_b32 s54, s67, s54
	s_lshl_b32 s54, s54, 8
	s_lshr_b32 s55, s60, 3
	s_lshl_b32 s55, s55, 13
	s_add_i32 s54, s54, s55
	s_lshr_b32 s55, s85, 1
	s_add_i32 s54, s54, s55
	s_and_b32 s57, s60, 7
	s_bitcmp1_b32 s75, 0
	s_cbranch_scc0 .Lmy_t_q
.Lmy_t_q:
	s_add_i32 s52, s75, 1
	s_cmp_ge_u32 s52, 8
	s_cbranch_scc1 .Lmy_t_last
	s_and_b32 s53, s52, 1
	s_lshr_b32 s52, s52, 1
	s_mov_b32 s54, s66
	s_cmp_eq_u32 s52, 1
	s_cselect_b32 s54, s61, s54
	s_cmp_eq_u32 s52, 2
	s_cselect_b32 s54, s63, s54
	s_cmp_eq_u32 s52, 3
	s_cselect_b32 s54, s67, s54
	s_lshl_b32 s54, s54, 8
	s_lshr_b32 s55, s60, 3
	s_lshl_b32 s55, s55, 13
	s_add_i32 s54, s54, s55
	s_lshr_b32 s55, s85, 1
	s_add_i32 s54, s54, s55
	s_lshl_b32 s56, s54, 11
	s_lshl_b32 s55, s57, 1
	s_add_i32 s55, s55, s53
	s_lshl_b32 s55, s55, 7
	s_add_u32 s56, s56, s55
	s_add_u32 s56, s56, 0x2800000
	s_add_u32 s58, s22, s56
	s_addc_u32 s59, s23, 0
	v_lshlrev_b32_e32 v254, 11, v212
	v_lshl_or_b32 v254, v213, 6, v254
	global_load_dword v255, v254, s[58:59]
